# MLA tile loop: K fragment LDS reads issued right after the tile barrier (LDS bases via SALU), half-steps 0 and 7 lead with the PV MFMAs whose operands are in registers, next tile V LDS stores moved ah
# speedup vs baseline: 1.0090x; 1.0090x over previous
; #define MFMA(a, b, c) __builtin_amdgcn_mfma_f32_32x32x16_bf16((a), (b), (c), 0, 0, 0)
;   DI u16* kt() const { return (u16*)(ws + O_KT); }
; DI void mla_item(const Ctx& c, int b, int head, int qblk) {
;     ...
;   for (int kt = 0; kt < ntile; ++kt) {
;     const int buf = kt & 1;
;     if (kt + 1 < ntile) MGLOADK((kt + 1) * 128);
; #pragma unroll 2
;     for (int kk = 0; kk < 4; ++kk) {
;       f32x16 s[2];
;       zero_acc(s[0]); zero_acc(s[1]);
; #pragma unroll
;       for (int ks = 0; ks < 6; ++ks) {
;         const bf16x8 kf = *(const bf16x8*)&Ks[buf][kk * 32 + pr][ks * 16 + hh * 8];
;         s[0] = MFMA(kf, qf[0][ks], s[0]);
;         s[1] = MFMA(kf, qf[1][ks], s[1]);
;       }
;       bf16x8 pf[2][2];
; #pragma unroll
;       for (int qt = 0; qt < 2; ++qt) {
;         float ls = 0.f;
; #pragma unroll
;         for (int i = 0; i < 16; ++i) { s[qt][i] = __builtin_amdgcn_exp2f(s[qt][i]); ls += s[qt][i]; }
;         lsum[qt] += ls;
;         pf[qt][0] = pack8(s[qt], 0);
;         pf[qt][1] = pack8(s[qt], 1);
;       }
; #pragma unroll
;       for (int dt = 0; dt < 2; ++dt)
; #pragma unroll
;         for (int s2 = 0; s2 < 2; ++s2) {
;           const bf16x8 vf = *(const bf16x8*)&Vs[buf][dt * 32 + r32][kk * 32 + s2 * 16 + hh * 8];
;           o[dt][0] = MFMA(vf, pf[0][s2], o[dt][0]);
;           o[dt][1] = MFMA(vf, pf[1][s2], o[dt][1]);
;         }
;       if (kk == 1 && kt + 1 < ntile) {
;         MSTOREK(buf ^ 1);
;         MGLOADV((kt + 1) * 128);
;       }
;     }
;     if (kt + 1 < ntile) MSTOREV(buf ^ 1);
;     __syncthreads();
.LBB0_404:
	s_and_b32 s17, s2, 0x6800
	v_add_u32_e32 v244, s17, v243
	s_and_b32 s17, s2, 0x4400
	v_add_u32_e32 v240, s17, v167
	ds_read_b128 v[182:185], v244 offset:0
	ds_read_b128 v[186:189], v244 offset:32
	ds_read_b128 v[190:193], v244 offset:64
	ds_read_b128 v[194:197], v244 offset:96
	ds_read_b128 v[198:201], v244 offset:128
	ds_read_b128 v[202:205], v244 offset:160
	s_add_i32 s15, s16, 1
	s_cmp_ge_u32 s15, s13
	s_cselect_b64 s[10:11], -1, 0
	s_cmp_lt_u32 s15, s13
	s_cselect_b64 s[8:9], -1, 0
	s_mov_b32 s21, s43
	s_lshl_b32 s20, s15, 7
	s_and_b64 vcc, exec, s[10:11]
	s_cbranch_vccnz .LBB0_406
	s_lshl_b64 s[18:19], s[20:21], 6
	v_lshl_add_u64 v[80:81], v[176:177], 0, s[18:19]
	s_lshl_b64 s[18:19], s[20:21], 7
	s_add_u32 s18, s4, s18
	s_addc_u32 s19, s5, s19
	v_lshl_add_u64 v[84:85], v[164:165], 1, s[18:19]
	v_lshl_add_u64 v[82:83], v[170:171], 1, s[18:19]
	global_load_dwordx4 v[148:151], v[84:85], off
	global_load_dwordx4 v[160:163], v[82:83], off
	global_load_dwordx4 v[152:155], v[80:81], off
.LBB0_406:
	s_andn2_b32 s16, 1, s16
	s_lshl_b64 s[18:19], s[20:21], 1
	s_mul_i32 s17, s16, 0x6800
	v_lshlrev_b32_e32 v80, 1, v247
	s_add_u32 s18, s6, s18
	v_add3_u32 v166, s17, v249, v80
	v_lshlrev_b32_e32 v80, 1, v248
	s_addc_u32 s19, s7, s19
	v_add3_u32 v245, s17, v241, v80
	s_mov_b32 s43, s21
	v_lshl_add_u64 v[178:179], v[172:173], 1, s[18:19]
	v_lshl_add_u64 v[180:181], v[174:175], 1, s[18:19]
	s_mov_b32 s17, 0
	s_xor_b64 s[10:11], s[10:11], -1
	s_branch .LBB0_408
.LBB0_408:
	v_mfma_f32_32x32x16_bf16 v[48:63], v[206:209], v[222:225], v[48:63]
	v_exp_f32_e32 v64, v64
	v_exp_f32_e32 v65, v65
	v_exp_f32_e32 v66, v66
	v_mfma_f32_32x32x16_bf16 v[32:47], v[214:217], v[222:225], v[32:47]
	v_exp_f32_e32 v67, v67
	v_exp_f32_e32 v68, v68
	v_exp_f32_e32 v69, v69
	v_mfma_f32_32x32x16_bf16 v[48:63], v[210:213], v[226:229], v[48:63]
	v_exp_f32_e32 v70, v70
	v_exp_f32_e32 v71, v71
	v_cvt_pk_bf16_f32 v230, v64, v65
	v_cvt_pk_bf16_f32 v231, v66, v67
	v_mfma_f32_32x32x16_bf16 v[32:47], v[218:221], v[226:229], v[32:47]
	v_exp_f32_e32 v72, v72
	v_exp_f32_e32 v73, v73
	v_cvt_pk_bf16_f32 v232, v68, v69
	v_cvt_pk_bf16_f32 v233, v70, v71
	s_waitcnt lgkmcnt(0)
	v_mfma_f32_32x32x16_bf16 v[80:95], v[182:185], v[96:99], 0
	v_mfma_f32_32x32x16_bf16 v[80:95], v[186:189], v[100:103], v[80:95]
	v_mfma_f32_32x32x16_bf16 v[80:95], v[190:193], v[104:107], v[80:95]
	v_exp_f32_e32 v74, v74
	v_exp_f32_e32 v75, v75
	v_add_f32_e32 v168, v168, v64
	v_add_f32_e32 v168, v168, v65
	v_mfma_f32_32x32x16_bf16 v[80:95], v[194:197], v[108:111], v[80:95]
	v_exp_f32_e32 v76, v76
	v_exp_f32_e32 v77, v77
	v_add_f32_e32 v168, v168, v66
	v_add_f32_e32 v168, v168, v67
	v_mfma_f32_32x32x16_bf16 v[80:95], v[198:201], v[112:115], v[80:95]
	v_exp_f32_e32 v78, v78
	v_exp_f32_e32 v79, v79
	v_add_f32_e32 v168, v168, v68
	v_add_f32_e32 v168, v168, v69
	v_mfma_f32_32x32x16_bf16 v[80:95], v[202:205], v[116:119], v[80:95]
	v_cvt_pk_bf16_f32 v234, v72, v73
	v_cvt_pk_bf16_f32 v235, v74, v75
	v_add_f32_e32 v168, v168, v70
	v_add_f32_e32 v168, v168, v71
	v_add_f32_e32 v168, v168, v72
	v_cvt_pk_bf16_f32 v236, v76, v77
	v_cvt_pk_bf16_f32 v237, v78, v79
	v_add_f32_e32 v168, v168, v73
	v_add_f32_e32 v168, v168, v74
	v_add_f32_e32 v168, v168, v75
	v_add_f32_e32 v168, v168, v76
	v_add_f32_e32 v168, v168, v77
	v_add_f32_e32 v168, v168, v78
	v_add_f32_e32 v168, v168, v79
	v_mfma_f32_32x32x16_bf16 v[64:79], v[182:185], v[120:123], 0
	v_exp_f32_e32 v80, v80
	v_exp_f32_e32 v81, v81
	v_exp_f32_e32 v82, v82
	v_mfma_f32_32x32x16_bf16 v[64:79], v[186:189], v[124:127], v[64:79]
	v_exp_f32_e32 v83, v83
	v_exp_f32_e32 v84, v84
	v_exp_f32_e32 v85, v85
	v_mfma_f32_32x32x16_bf16 v[64:79], v[190:193], v[128:131], v[64:79]
	v_exp_f32_e32 v86, v86
	v_exp_f32_e32 v87, v87
	v_cvt_pk_bf16_f32 v222, v80, v81
	v_cvt_pk_bf16_f32 v223, v82, v83
	v_mfma_f32_32x32x16_bf16 v[64:79], v[194:197], v[132:135], v[64:79]
	v_exp_f32_e32 v88, v88
	v_exp_f32_e32 v89, v89
	v_cvt_pk_bf16_f32 v224, v84, v85
	v_cvt_pk_bf16_f32 v225, v86, v87
	v_mfma_f32_32x32x16_bf16 v[64:79], v[198:201], v[136:139], v[64:79]
	v_exp_f32_e32 v90, v90
	v_exp_f32_e32 v91, v91
	v_add_f32_e32 v169, v169, v80
	v_add_f32_e32 v169, v169, v81
	v_mfma_f32_32x32x16_bf16 v[64:79], v[202:205], v[140:143], v[64:79]
	v_exp_f32_e32 v92, v92
	v_exp_f32_e32 v93, v93
	v_add_f32_e32 v169, v169, v82
	v_add_f32_e32 v169, v169, v83
	ds_read_b128 v[182:185], v244 offset:6656
	ds_read_b128 v[186:189], v244 offset:6688
	ds_read_b128 v[190:193], v244 offset:6720
	ds_read_b128 v[194:197], v244 offset:6752
	ds_read_b128 v[198:201], v244 offset:6784
	ds_read_b128 v[202:205], v244 offset:6816
	v_mfma_f32_32x32x16_bf16 v[16:31], v[206:209], v[230:233], v[16:31]
	v_exp_f32_e32 v94, v94
	v_exp_f32_e32 v95, v95
	v_add_f32_e32 v169, v169, v84
	v_add_f32_e32 v169, v169, v85
	v_mfma_f32_32x32x16_bf16 v[0:15], v[214:217], v[230:233], v[0:15]
	v_cvt_pk_bf16_f32 v226, v88, v89
	v_cvt_pk_bf16_f32 v227, v90, v91
	v_add_f32_e32 v169, v169, v86
	v_add_f32_e32 v169, v169, v87
	v_add_f32_e32 v169, v169, v88
	v_mfma_f32_32x32x16_bf16 v[16:31], v[210:213], v[234:237], v[16:31]
	v_cvt_pk_bf16_f32 v228, v92, v93
	v_cvt_pk_bf16_f32 v229, v94, v95
	v_add_f32_e32 v169, v169, v89
	v_add_f32_e32 v169, v169, v90
	v_add_f32_e32 v169, v169, v91
	v_mfma_f32_32x32x16_bf16 v[0:15], v[218:221], v[234:237], v[0:15]
	v_add_f32_e32 v169, v169, v92
	v_add_f32_e32 v169, v169, v93
	v_add_f32_e32 v169, v169, v94
	v_add_f32_e32 v169, v169, v95
	ds_read_b128 v[206:209], v240 offset:0
	ds_read_b128 v[210:213], v240 offset:32
	ds_read_b128 v[214:217], v240 offset:8704
	ds_read_b128 v[218:221], v240 offset:8736
	s_waitcnt lgkmcnt(4)
; #define MFMA(a, b, c) __builtin_amdgcn_mfma_f32_32x32x16_bf16((a), (b), (c), 0, 0, 0)
;   DI u16* kt() const { return (u16*)(ws + O_KT); }
; DI void mla_item(const Ctx& c, int b, int head, int qblk) {
;     ...
;     for (int kk = 0; kk < 4; ++kk) {
;       f32x16 s[2];
;       zero_acc(s[0]); zero_acc(s[1]);
; #pragma unroll
;       for (int ks = 0; ks < 6; ++ks) {
;         const bf16x8 kf = *(const bf16x8*)&Ks[buf][kk * 32 + pr][ks * 16 + hh * 8];
;         s[0] = MFMA(kf, qf[0][ks], s[0]);
;         s[1] = MFMA(kf, qf[1][ks], s[1]);
;       }
;       bf16x8 pf[2][2];
; #pragma unroll
;       for (int qt = 0; qt < 2; ++qt) {
;         float ls = 0.f;
; #pragma unroll
;         for (int i = 0; i < 16; ++i) { s[qt][i] = __builtin_amdgcn_exp2f(s[qt][i]); ls += s[qt][i]; }
;         lsum[qt] += ls;
;         pf[qt][0] = pack8(s[qt], 0);
;         pf[qt][1] = pack8(s[qt], 1);
;       }
; #pragma unroll
;       for (int dt = 0; dt < 2; ++dt)
; #pragma unroll
;         for (int s2 = 0; s2 < 2; ++s2) {
;           const bf16x8 vf = *(const bf16x8*)&Vs[buf][dt * 32 + r32][kk * 32 + s2 * 16 + hh * 8];
;           o[dt][0] = MFMA(vf, pf[0][s2], o[dt][0]);
;           o[dt][1] = MFMA(vf, pf[1][s2], o[dt][1]);
;         }
;       if (kk == 1 && kt + 1 < ntile) {
;         MSTOREK(buf ^ 1);
;         MGLOADV((kt + 1) * 128);
;       }
	v_mfma_f32_32x32x16_bf16 v[80:95], v[182:185], v[96:99], 0
	v_exp_f32_e32 v64, v64
	v_exp_f32_e32 v65, v65
	v_exp_f32_e32 v66, v66
	v_mfma_f32_32x32x16_bf16 v[80:95], v[186:189], v[100:103], v[80:95]
	v_exp_f32_e32 v67, v67
	v_exp_f32_e32 v68, v68
	v_exp_f32_e32 v69, v69
	v_mfma_f32_32x32x16_bf16 v[80:95], v[190:193], v[104:107], v[80:95]
	v_exp_f32_e32 v70, v70
	v_exp_f32_e32 v71, v71
	v_cvt_pk_bf16_f32 v230, v64, v65
	v_cvt_pk_bf16_f32 v231, v66, v67
	v_mfma_f32_32x32x16_bf16 v[80:95], v[194:197], v[108:111], v[80:95]
	v_exp_f32_e32 v72, v72
	v_exp_f32_e32 v73, v73
	v_cvt_pk_bf16_f32 v232, v68, v69
	v_cvt_pk_bf16_f32 v233, v70, v71
	v_mfma_f32_32x32x16_bf16 v[80:95], v[198:201], v[112:115], v[80:95]
	v_exp_f32_e32 v74, v74
	v_exp_f32_e32 v75, v75
	v_add_f32_e32 v168, v168, v64
	v_add_f32_e32 v168, v168, v65
	v_mfma_f32_32x32x16_bf16 v[80:95], v[202:205], v[116:119], v[80:95]
	v_exp_f32_e32 v76, v76
	v_exp_f32_e32 v77, v77
	v_add_f32_e32 v168, v168, v66
	v_add_f32_e32 v168, v168, v67
	s_waitcnt lgkmcnt(0)
	v_mfma_f32_32x32x16_bf16 v[48:63], v[206:209], v[222:225], v[48:63]
	v_exp_f32_e32 v78, v78
	v_exp_f32_e32 v79, v79
	v_add_f32_e32 v168, v168, v68
	v_add_f32_e32 v168, v168, v69
	v_mfma_f32_32x32x16_bf16 v[32:47], v[214:217], v[222:225], v[32:47]
	v_cvt_pk_bf16_f32 v234, v72, v73
	v_cvt_pk_bf16_f32 v235, v74, v75
	v_add_f32_e32 v168, v168, v70
	v_add_f32_e32 v168, v168, v71
	v_add_f32_e32 v168, v168, v72
	v_mfma_f32_32x32x16_bf16 v[48:63], v[210:213], v[226:229], v[48:63]
	v_cvt_pk_bf16_f32 v236, v76, v77
	v_cvt_pk_bf16_f32 v237, v78, v79
	v_add_f32_e32 v168, v168, v73
	v_add_f32_e32 v168, v168, v74
	v_add_f32_e32 v168, v168, v75
	v_mfma_f32_32x32x16_bf16 v[32:47], v[218:221], v[226:229], v[32:47]
	v_add_f32_e32 v168, v168, v76
	v_add_f32_e32 v168, v168, v77
	v_add_f32_e32 v168, v168, v78
	v_add_f32_e32 v168, v168, v79
	v_mfma_f32_32x32x16_bf16 v[64:79], v[182:185], v[120:123], 0
	v_exp_f32_e32 v80, v80
	v_exp_f32_e32 v81, v81
	v_exp_f32_e32 v82, v82
	v_mfma_f32_32x32x16_bf16 v[64:79], v[186:189], v[124:127], v[64:79]
	v_exp_f32_e32 v83, v83
	v_exp_f32_e32 v84, v84
	v_exp_f32_e32 v85, v85
	v_mfma_f32_32x32x16_bf16 v[64:79], v[190:193], v[128:131], v[64:79]
	v_exp_f32_e32 v86, v86
	v_exp_f32_e32 v87, v87
	v_cvt_pk_bf16_f32 v222, v80, v81
	v_cvt_pk_bf16_f32 v223, v82, v83
	v_mfma_f32_32x32x16_bf16 v[64:79], v[194:197], v[132:135], v[64:79]
	v_exp_f32_e32 v88, v88
	v_exp_f32_e32 v89, v89
	v_cvt_pk_bf16_f32 v224, v84, v85
	v_cvt_pk_bf16_f32 v225, v86, v87
	v_mfma_f32_32x32x16_bf16 v[64:79], v[198:201], v[136:139], v[64:79]
	v_exp_f32_e32 v90, v90
	v_exp_f32_e32 v91, v91
	v_add_f32_e32 v169, v169, v80
	v_add_f32_e32 v169, v169, v81
	v_mfma_f32_32x32x16_bf16 v[64:79], v[202:205], v[140:143], v[64:79]
	v_exp_f32_e32 v92, v92
	v_exp_f32_e32 v93, v93
	v_add_f32_e32 v169, v169, v82
	v_add_f32_e32 v169, v169, v83
	ds_read_b128 v[182:185], v244 offset:13312
	ds_read_b128 v[186:189], v244 offset:13344
	ds_read_b128 v[190:193], v244 offset:13376
	ds_read_b128 v[194:197], v244 offset:13408
	ds_read_b128 v[198:201], v244 offset:13440
	ds_read_b128 v[202:205], v244 offset:13472
	v_mfma_f32_32x32x16_bf16 v[16:31], v[206:209], v[230:233], v[16:31]
	v_exp_f32_e32 v94, v94
	v_exp_f32_e32 v95, v95
	v_add_f32_e32 v169, v169, v84
	v_add_f32_e32 v169, v169, v85
	v_mfma_f32_32x32x16_bf16 v[0:15], v[214:217], v[230:233], v[0:15]
	v_cvt_pk_bf16_f32 v226, v88, v89
	v_cvt_pk_bf16_f32 v227, v90, v91
	v_add_f32_e32 v169, v169, v86
	v_add_f32_e32 v169, v169, v87
	v_add_f32_e32 v169, v169, v88
	v_mfma_f32_32x32x16_bf16 v[16:31], v[210:213], v[234:237], v[16:31]
	v_cvt_pk_bf16_f32 v228, v92, v93
	v_cvt_pk_bf16_f32 v229, v94, v95
	v_add_f32_e32 v169, v169, v89
	v_add_f32_e32 v169, v169, v90
	v_add_f32_e32 v169, v169, v91
	v_mfma_f32_32x32x16_bf16 v[0:15], v[218:221], v[234:237], v[0:15]
	v_add_f32_e32 v169, v169, v92
	v_add_f32_e32 v169, v169, v93
	v_add_f32_e32 v169, v169, v94
	v_add_f32_e32 v169, v169, v95
	ds_read_b128 v[206:209], v240 offset:64
	ds_read_b128 v[210:213], v240 offset:96
	ds_read_b128 v[214:217], v240 offset:8768
	ds_read_b128 v[218:221], v240 offset:8800
	s_and_b64 vcc, exec, s[10:11]
	s_cbranch_vccz .Lmla_mid_done
	global_load_dwordx4 v[144:147], v[178:179], off
	global_load_dwordx4 v[156:159], v[180:181], off
	s_waitcnt vmcnt(2)
	ds_write_b128 v166, v[148:151]
	ds_write_b128 v166, v[160:163] offset:13312
	ds_write_b128 v245, v[152:155] offset:128
; #define MFMA(a, b, c) __builtin_amdgcn_mfma_f32_32x32x16_bf16((a), (b), (c), 0, 0, 0)
;   DI u16* kt() const { return (u16*)(ws + O_KT); }
; DI void mla_item(const Ctx& c, int b, int head, int qblk) {
;     ...
;     for (int kk = 0; kk < 4; ++kk) {
;       f32x16 s[2];
;       zero_acc(s[0]); zero_acc(s[1]);
; #pragma unroll
;       for (int ks = 0; ks < 6; ++ks) {
;         const bf16x8 kf = *(const bf16x8*)&Ks[buf][kk * 32 + pr][ks * 16 + hh * 8];
;         s[0] = MFMA(kf, qf[0][ks], s[0]);
;         s[1] = MFMA(kf, qf[1][ks], s[1]);
;       }
;       bf16x8 pf[2][2];
; #pragma unroll
;       for (int qt = 0; qt < 2; ++qt) {
;         float ls = 0.f;
; #pragma unroll
;         for (int i = 0; i < 16; ++i) { s[qt][i] = __builtin_amdgcn_exp2f(s[qt][i]); ls += s[qt][i]; }
;         lsum[qt] += ls;
;         pf[qt][0] = pack8(s[qt], 0);
;         pf[qt][1] = pack8(s[qt], 1);
;       }
; #pragma unroll
;       for (int dt = 0; dt < 2; ++dt)
; #pragma unroll
;         for (int s2 = 0; s2 < 2; ++s2) {
;           const bf16x8 vf = *(const bf16x8*)&Vs[buf][dt * 32 + r32][kk * 32 + s2 * 16 + hh * 8];
;           o[dt][0] = MFMA(vf, pf[0][s2], o[dt][0]);
;           o[dt][1] = MFMA(vf, pf[1][s2], o[dt][1]);
;         }
;       if (kk == 1 && kt + 1 < ntile) {
;         MSTOREK(buf ^ 1);
;         MGLOADV((kt + 1) * 128);
;       }
;     }
;     if (kt + 1 < ntile) MSTOREV(buf ^ 1);
.Lmla_mid_done:
	s_waitcnt lgkmcnt(4)
	v_mfma_f32_32x32x16_bf16 v[80:95], v[182:185], v[96:99], 0
	v_exp_f32_e32 v64, v64
	v_exp_f32_e32 v65, v65
	v_exp_f32_e32 v66, v66
	v_mfma_f32_32x32x16_bf16 v[80:95], v[186:189], v[100:103], v[80:95]
	v_exp_f32_e32 v67, v67
	v_exp_f32_e32 v68, v68
	v_exp_f32_e32 v69, v69
	v_mfma_f32_32x32x16_bf16 v[80:95], v[190:193], v[104:107], v[80:95]
	v_exp_f32_e32 v70, v70
	v_exp_f32_e32 v71, v71
	v_cvt_pk_bf16_f32 v230, v64, v65
	v_cvt_pk_bf16_f32 v231, v66, v67
	v_mfma_f32_32x32x16_bf16 v[80:95], v[194:197], v[108:111], v[80:95]
	v_exp_f32_e32 v72, v72
	v_exp_f32_e32 v73, v73
	v_cvt_pk_bf16_f32 v232, v68, v69
	v_cvt_pk_bf16_f32 v233, v70, v71
	v_mfma_f32_32x32x16_bf16 v[80:95], v[198:201], v[112:115], v[80:95]
	v_exp_f32_e32 v74, v74
	v_exp_f32_e32 v75, v75
	v_add_f32_e32 v168, v168, v64
	v_add_f32_e32 v168, v168, v65
	v_mfma_f32_32x32x16_bf16 v[80:95], v[202:205], v[116:119], v[80:95]
	v_exp_f32_e32 v76, v76
	v_exp_f32_e32 v77, v77
	v_add_f32_e32 v168, v168, v66
	v_add_f32_e32 v168, v168, v67
	s_waitcnt lgkmcnt(0)
	v_mfma_f32_32x32x16_bf16 v[48:63], v[206:209], v[222:225], v[48:63]
	v_exp_f32_e32 v78, v78
	v_exp_f32_e32 v79, v79
	v_add_f32_e32 v168, v168, v68
	v_add_f32_e32 v168, v168, v69
	v_mfma_f32_32x32x16_bf16 v[32:47], v[214:217], v[222:225], v[32:47]
	v_cvt_pk_bf16_f32 v234, v72, v73
	v_cvt_pk_bf16_f32 v235, v74, v75
	v_add_f32_e32 v168, v168, v70
	v_add_f32_e32 v168, v168, v71
	v_add_f32_e32 v168, v168, v72
	v_mfma_f32_32x32x16_bf16 v[48:63], v[210:213], v[226:229], v[48:63]
	v_cvt_pk_bf16_f32 v236, v76, v77
	v_cvt_pk_bf16_f32 v237, v78, v79
	v_add_f32_e32 v168, v168, v73
	v_add_f32_e32 v168, v168, v74
	v_add_f32_e32 v168, v168, v75
	v_mfma_f32_32x32x16_bf16 v[32:47], v[218:221], v[226:229], v[32:47]
	v_add_f32_e32 v168, v168, v76
	v_add_f32_e32 v168, v168, v77
	v_add_f32_e32 v168, v168, v78
	v_add_f32_e32 v168, v168, v79
	v_mfma_f32_32x32x16_bf16 v[64:79], v[182:185], v[120:123], 0
	v_exp_f32_e32 v80, v80
	v_exp_f32_e32 v81, v81
	v_exp_f32_e32 v82, v82
	v_mfma_f32_32x32x16_bf16 v[64:79], v[186:189], v[124:127], v[64:79]
	v_exp_f32_e32 v83, v83
	v_exp_f32_e32 v84, v84
	v_exp_f32_e32 v85, v85
	v_mfma_f32_32x32x16_bf16 v[64:79], v[190:193], v[128:131], v[64:79]
	v_exp_f32_e32 v86, v86
	v_exp_f32_e32 v87, v87
	v_cvt_pk_bf16_f32 v222, v80, v81
	v_cvt_pk_bf16_f32 v223, v82, v83
	v_mfma_f32_32x32x16_bf16 v[64:79], v[194:197], v[132:135], v[64:79]
	v_exp_f32_e32 v88, v88
	v_exp_f32_e32 v89, v89
	v_cvt_pk_bf16_f32 v224, v84, v85
	v_cvt_pk_bf16_f32 v225, v86, v87
	v_mfma_f32_32x32x16_bf16 v[64:79], v[198:201], v[136:139], v[64:79]
	v_exp_f32_e32 v90, v90
	v_exp_f32_e32 v91, v91
	v_add_f32_e32 v169, v169, v80
	v_add_f32_e32 v169, v169, v81
	v_mfma_f32_32x32x16_bf16 v[64:79], v[202:205], v[140:143], v[64:79]
	v_exp_f32_e32 v92, v92
	v_exp_f32_e32 v93, v93
	v_add_f32_e32 v169, v169, v82
	v_add_f32_e32 v169, v169, v83
	ds_read_b128 v[182:185], v244 offset:19968
	ds_read_b128 v[186:189], v244 offset:20000
	ds_read_b128 v[190:193], v244 offset:20032
	ds_read_b128 v[194:197], v244 offset:20064
	ds_read_b128 v[198:201], v244 offset:20096
	ds_read_b128 v[202:205], v244 offset:20128
	v_mfma_f32_32x32x16_bf16 v[16:31], v[206:209], v[230:233], v[16:31]
	v_exp_f32_e32 v94, v94
	v_exp_f32_e32 v95, v95
	v_add_f32_e32 v169, v169, v84
	v_add_f32_e32 v169, v169, v85
	v_mfma_f32_32x32x16_bf16 v[0:15], v[214:217], v[230:233], v[0:15]
	v_cvt_pk_bf16_f32 v226, v88, v89
	v_cvt_pk_bf16_f32 v227, v90, v91
	v_add_f32_e32 v169, v169, v86
	v_add_f32_e32 v169, v169, v87
	v_add_f32_e32 v169, v169, v88
	v_mfma_f32_32x32x16_bf16 v[16:31], v[210:213], v[234:237], v[16:31]
	v_cvt_pk_bf16_f32 v228, v92, v93
	v_cvt_pk_bf16_f32 v229, v94, v95
	v_add_f32_e32 v169, v169, v89
	v_add_f32_e32 v169, v169, v90
	v_add_f32_e32 v169, v169, v91
	v_mfma_f32_32x32x16_bf16 v[0:15], v[218:221], v[234:237], v[0:15]
	v_add_f32_e32 v169, v169, v92
	v_add_f32_e32 v169, v169, v93
	v_add_f32_e32 v169, v169, v94
	v_add_f32_e32 v169, v169, v95
	ds_read_b128 v[206:209], v240 offset:128
	ds_read_b128 v[210:213], v240 offset:160
	ds_read_b128 v[214:217], v240 offset:8832
	ds_read_b128 v[218:221], v240 offset:8864
	s_waitcnt lgkmcnt(4)
	v_mfma_f32_32x32x16_bf16 v[80:95], v[182:185], v[96:99], 0
	v_exp_f32_e32 v64, v64
	v_exp_f32_e32 v65, v65
	v_exp_f32_e32 v66, v66
	v_mfma_f32_32x32x16_bf16 v[80:95], v[186:189], v[100:103], v[80:95]
	v_exp_f32_e32 v67, v67
	v_exp_f32_e32 v68, v68
	v_exp_f32_e32 v69, v69
	v_mfma_f32_32x32x16_bf16 v[80:95], v[190:193], v[104:107], v[80:95]
	v_exp_f32_e32 v70, v70
	v_exp_f32_e32 v71, v71
	v_cvt_pk_bf16_f32 v230, v64, v65
	v_cvt_pk_bf16_f32 v231, v66, v67
	v_mfma_f32_32x32x16_bf16 v[80:95], v[194:197], v[108:111], v[80:95]
	v_exp_f32_e32 v72, v72
	v_exp_f32_e32 v73, v73
	v_cvt_pk_bf16_f32 v232, v68, v69
	v_cvt_pk_bf16_f32 v233, v70, v71
	v_mfma_f32_32x32x16_bf16 v[80:95], v[198:201], v[112:115], v[80:95]
	v_exp_f32_e32 v74, v74
	v_exp_f32_e32 v75, v75
	v_add_f32_e32 v168, v168, v64
	v_add_f32_e32 v168, v168, v65
	v_mfma_f32_32x32x16_bf16 v[80:95], v[202:205], v[116:119], v[80:95]
	v_exp_f32_e32 v76, v76
	v_exp_f32_e32 v77, v77
	v_add_f32_e32 v168, v168, v66
	v_add_f32_e32 v168, v168, v67
	s_waitcnt lgkmcnt(0)
	v_mfma_f32_32x32x16_bf16 v[48:63], v[206:209], v[222:225], v[48:63]
	v_exp_f32_e32 v78, v78
	v_exp_f32_e32 v79, v79
	v_add_f32_e32 v168, v168, v68
	v_add_f32_e32 v168, v168, v69
	v_mfma_f32_32x32x16_bf16 v[32:47], v[214:217], v[222:225], v[32:47]
	v_cvt_pk_bf16_f32 v234, v72, v73
	v_cvt_pk_bf16_f32 v235, v74, v75
	v_add_f32_e32 v168, v168, v70
	v_add_f32_e32 v168, v168, v71
	v_add_f32_e32 v168, v168, v72
	v_mfma_f32_32x32x16_bf16 v[48:63], v[210:213], v[226:229], v[48:63]
	v_cvt_pk_bf16_f32 v236, v76, v77
	v_cvt_pk_bf16_f32 v237, v78, v79
	v_add_f32_e32 v168, v168, v73
	v_add_f32_e32 v168, v168, v74
	v_add_f32_e32 v168, v168, v75
	v_mfma_f32_32x32x16_bf16 v[32:47], v[218:221], v[226:229], v[32:47]
	v_add_f32_e32 v168, v168, v76
	v_add_f32_e32 v168, v168, v77
	v_add_f32_e32 v168, v168, v78
	v_add_f32_e32 v168, v168, v79
	s_and_b64 vcc, exec, s[8:9]
	s_cbranch_vccz .Lmla_vst_done
	s_mulk_i32 s16, 0x4400
	v_add_u32_e32 v246, s16, v242
	s_waitcnt vmcnt(1)
	ds_write_b128 v246, v[144:147] offset:53248
	s_waitcnt vmcnt(0)
	ds_write_b128 v246, v[156:159] offset:61952
; #define MFMA(a, b, c) __builtin_amdgcn_mfma_f32_32x32x16_bf16((a), (b), (c), 0, 0, 0)
;   DI u16* kt() const { return (u16*)(ws + O_KT); }
; DI void mla_item(const Ctx& c, int b, int head, int qblk) {
;     ...
;   for (int kt = 0; kt < ntile; ++kt) {
;     const int buf = kt & 1;
;     if (kt + 1 < ntile) MGLOADK((kt + 1) * 128);
; #pragma unroll 2
;     for (int kk = 0; kk < 4; ++kk) {
;       f32x16 s[2];
;       zero_acc(s[0]); zero_acc(s[1]);
; #pragma unroll
;       for (int ks = 0; ks < 6; ++ks) {
;         const bf16x8 kf = *(const bf16x8*)&Ks[buf][kk * 32 + pr][ks * 16 + hh * 8];
;         s[0] = MFMA(kf, qf[0][ks], s[0]);
;         s[1] = MFMA(kf, qf[1][ks], s[1]);
;       }
;       bf16x8 pf[2][2];
; #pragma unroll
;       for (int qt = 0; qt < 2; ++qt) {
;         float ls = 0.f;
; #pragma unroll
;         for (int i = 0; i < 16; ++i) { s[qt][i] = __builtin_amdgcn_exp2f(s[qt][i]); ls += s[qt][i]; }
;         lsum[qt] += ls;
;         pf[qt][0] = pack8(s[qt], 0);
;         pf[qt][1] = pack8(s[qt], 1);
;       }
; #pragma unroll
;       for (int dt = 0; dt < 2; ++dt)
; #pragma unroll
;         for (int s2 = 0; s2 < 2; ++s2) {
;           const bf16x8 vf = *(const bf16x8*)&Vs[buf][dt * 32 + r32][kk * 32 + s2 * 16 + hh * 8];
;           o[dt][0] = MFMA(vf, pf[0][s2], o[dt][0]);
;           o[dt][1] = MFMA(vf, pf[1][s2], o[dt][1]);
;         }
;       if (kk == 1 && kt + 1 < ntile) {
;         MSTOREK(buf ^ 1);
;         MGLOADV((kt + 1) * 128);
;       }
;     }
;     if (kt + 1 < ntile) MSTOREV(buf ^ 1);
;     __syncthreads();
;   }
.Lmla_vst_done:
	v_mfma_f32_32x32x16_bf16 v[16:31], v[206:209], v[230:233], v[16:31]
	v_exp_f32_e32 v80, v80
	v_exp_f32_e32 v81, v81
	v_exp_f32_e32 v82, v82
	v_mfma_f32_32x32x16_bf16 v[0:15], v[214:217], v[230:233], v[0:15]
	v_exp_f32_e32 v83, v83
	v_exp_f32_e32 v84, v84
	v_exp_f32_e32 v85, v85
	v_mfma_f32_32x32x16_bf16 v[16:31], v[210:213], v[234:237], v[16:31]
	v_exp_f32_e32 v86, v86
	v_exp_f32_e32 v87, v87
	v_cvt_pk_bf16_f32 v222, v80, v81
	v_cvt_pk_bf16_f32 v223, v82, v83
	v_mfma_f32_32x32x16_bf16 v[0:15], v[218:221], v[234:237], v[0:15]
	v_exp_f32_e32 v88, v88
	v_exp_f32_e32 v89, v89
	v_cvt_pk_bf16_f32 v224, v84, v85
	v_cvt_pk_bf16_f32 v225, v86, v87
	ds_read_b128 v[206:209], v240 offset:192
	ds_read_b128 v[210:213], v240 offset:224
	ds_read_b128 v[214:217], v240 offset:8896
	ds_read_b128 v[218:221], v240 offset:8928
	v_mfma_f32_32x32x16_bf16 v[64:79], v[182:185], v[120:123], 0
	v_exp_f32_e32 v90, v90
	v_exp_f32_e32 v91, v91
	v_add_f32_e32 v169, v169, v80
	v_add_f32_e32 v169, v169, v81
	v_mfma_f32_32x32x16_bf16 v[64:79], v[186:189], v[124:127], v[64:79]
	v_exp_f32_e32 v92, v92
	v_exp_f32_e32 v93, v93
	v_add_f32_e32 v169, v169, v82
	v_add_f32_e32 v169, v169, v83
	v_mfma_f32_32x32x16_bf16 v[64:79], v[190:193], v[128:131], v[64:79]
	v_exp_f32_e32 v94, v94
	v_exp_f32_e32 v95, v95
	v_add_f32_e32 v169, v169, v84
	v_add_f32_e32 v169, v169, v85
	v_mfma_f32_32x32x16_bf16 v[64:79], v[194:197], v[132:135], v[64:79]
	v_cvt_pk_bf16_f32 v226, v88, v89
	v_cvt_pk_bf16_f32 v227, v90, v91
	v_add_f32_e32 v169, v169, v86
	v_add_f32_e32 v169, v169, v87
	v_add_f32_e32 v169, v169, v88
	v_mfma_f32_32x32x16_bf16 v[64:79], v[198:201], v[136:139], v[64:79]
	v_cvt_pk_bf16_f32 v228, v92, v93
	v_cvt_pk_bf16_f32 v229, v94, v95
	v_add_f32_e32 v169, v169, v89
	v_add_f32_e32 v169, v169, v90
	v_add_f32_e32 v169, v169, v91
	v_mfma_f32_32x32x16_bf16 v[64:79], v[202:205], v[140:143], v[64:79]
	v_add_f32_e32 v169, v169, v92
	v_add_f32_e32 v169, v169, v93
	v_add_f32_e32 v169, v169, v94
	v_add_f32_e32 v169, v169, v95
	s_branch .LBB0_410
.Lmla_drain:
	s_nop 3
	v_mfma_f32_32x32x16_bf16 v[48:63], v[206:209], v[222:225], v[48:63]
	v_exp_f32_e32 v64, v64
	v_exp_f32_e32 v65, v65
	v_exp_f32_e32 v66, v66
	v_mfma_f32_32x32x16_bf16 v[32:47], v[214:217], v[222:225], v[32:47]
	v_exp_f32_e32 v67, v67
	v_exp_f32_e32 v68, v68
	v_exp_f32_e32 v69, v69
	v_mfma_f32_32x32x16_bf16 v[48:63], v[210:213], v[226:229], v[48:63]
	v_exp_f32_e32 v70, v70
	v_exp_f32_e32 v71, v71
	v_cvt_pk_bf16_f32 v230, v64, v65
	v_cvt_pk_bf16_f32 v231, v66, v67
	v_mfma_f32_32x32x16_bf16 v[32:47], v[218:221], v[226:229], v[32:47]
	v_exp_f32_e32 v72, v72
	v_exp_f32_e32 v73, v73
	v_cvt_pk_bf16_f32 v232, v68, v69
	v_cvt_pk_bf16_f32 v233, v70, v71
	v_exp_f32_e32 v74, v74
	v_exp_f32_e32 v75, v75
	v_add_f32_e32 v168, v168, v64
	v_add_f32_e32 v168, v168, v65
	v_exp_f32_e32 v76, v76
	v_exp_f32_e32 v77, v77
	v_add_f32_e32 v168, v168, v66
	v_add_f32_e32 v168, v168, v67
	v_exp_f32_e32 v78, v78
	v_exp_f32_e32 v79, v79
	v_add_f32_e32 v168, v168, v68
	v_add_f32_e32 v168, v168, v69
	v_cvt_pk_bf16_f32 v234, v72, v73
	v_cvt_pk_bf16_f32 v235, v74, v75
	v_add_f32_e32 v168, v168, v70
	v_add_f32_e32 v168, v168, v71
	v_add_f32_e32 v168, v168, v72
	v_cvt_pk_bf16_f32 v236, v76, v77
	v_cvt_pk_bf16_f32 v237, v78, v79
	v_add_f32_e32 v168, v168, v73
	v_add_f32_e32 v168, v168, v74
	v_add_f32_e32 v168, v168, v75
	v_add_f32_e32 v168, v168, v76
	v_add_f32_e32 v168, v168, v77
	v_add_f32_e32 v168, v168, v78
	v_add_f32_e32 v168, v168, v79
	v_mfma_f32_32x32x16_bf16 v[16:31], v[206:209], v[230:233], v[16:31]
	v_mfma_f32_32x32x16_bf16 v[0:15], v[214:217], v[230:233], v[0:15]
	v_mfma_f32_32x32x16_bf16 v[16:31], v[210:213], v[234:237], v[16:31]
	v_mfma_f32_32x32x16_bf16 v[0:15], v[218:221], v[234:237], v[0:15]
	s_branch .LBB0_398
.LBB0_410:
.LBB0_412:
	s_xor_b64 s[2:3], s[2:3], -1
	s_cmp_lg_u32 s15, s13
	s_waitcnt lgkmcnt(0)
	s_barrier
	s_cbranch_scc0 .Lmla_drain
	s_mov_b32 s16, s15
	s_branch .LBB0_404
